# write-through stores for the attention outputs too
# baseline (speedup 1.0000x reference)
; __device__ __forceinline__ void attn_phase(bf16_t* QKV, float* LSE, const float* rel_table, LAS unsigned char* lds, int bx, int Gd, int tid) {
;     ...
;         for (int c5 = 0; c5 < 5; ++c5) {
;             const int kbase = 32 * w + 32 * c5;
;             bf16x8 kf[2][2];
; #pragma unroll
;             for (int kt = 0; kt < 2; ++kt) { const int row = kbase + 16 * kt + fr;
; #pragma unroll
;                 for (int s2 = 0; s2 < 2; ++s2) kf[kt][s2] = *(const LAS bf16x8*)(lds + ATT_K + row * 128 + (((G + 4 * s2) ^ kswz(row)) * 16)); }
;             bf16x8 vf[4];
; #pragma unroll
;             for (int cc = 0; cc < 4; ++cc) {
;                 const int r0 = kbase + 4 * G + q4, r1 = r0 + 16;
;                 const s16x4 lo = __builtin_bit_cast(s16x4, __builtin_amdgcn_ds_read_tr16_b64_v4i16((LAS s16x4*)(lds + ATT_V + r0 * 128 + ((cc ^ ((r0 >> 1) & 3)) * 32) + 8 * p4)));
;                 const s16x4 hi = __builtin_bit_cast(s16x4, __builtin_amdgcn_ds_read_tr16_b64_v4i16((LAS s16x4*)(lds + ATT_V + r1 * 128 + ((cc ^ ((r1 >> 1) & 3)) * 32) + 8 * p4)));
;                 vf[cc] = (bf16x8){lo[0], lo[1], lo[2], lo[3], hi[0], hi[1], hi[2], hi[3]}; }
;             const bool edge = (c.qt == 0) && (kbase < 128);
; #pragma unroll
;             for (int qi = 0; qi < 2; ++qi) {
;                 f32x4 S[2];
; #pragma unroll
;                 for (int kt = 0; kt < 2; ++kt) { S[kt] = __builtin_amdgcn_mfma_f32_16x16x32_bf16(kf[kt][0], qf[qi][0], (f32x4){0.f, 0.f, 0.f, 0.f}, 0, 0, 0);
;                     S[kt] = __builtin_amdgcn_mfma_f32_16x16x32_bf16(kf[kt][1], qf[qi][1], S[kt], 0, 0, 0); }
;                 float mx = -1e30f;
; #pragma unroll
;                 for (int kt = 0; kt < 2; ++kt)
; #pragma unroll
;                     for (int i = 0; i < 4; ++i) { const int li = 159 + 16 * qi + fr - 4 * G - 32 * c5 - 16 * kt - i;
;                         float sv = S[kt][i] * c1 + lut[li];
;                         if (edge && (kbase + 16 * kt + 4 * G + i) < 128) sv = -1e30f;
;                         S[kt][i] = sv; mx = fmaxf(mx, sv); }
;                 mx = fmaxf(mx, __shfl_xor(mx, 16)); mx = fmaxf(mx, __shfl_xor(mx, 32));
;                 const float mnew = fmaxf(mrun[qi], mx), alpha = fast_exp2(mrun[qi] - mnew); mrun[qi] = mnew;
;                 float ps = 0.f;
; #pragma unroll
;                 for (int kt = 0; kt < 2; ++kt)
; #pragma unroll
.LBB0_119:
	v_add_u32_e32 v112, 0, v173
	ds_read_b128 v[176:179], v112
	v_mov_b32_e32 v214, v163
	v_add_u32_e32 v113, 0, v171
	v_add_u32_e32 v114, 0, v168
	v_add_u32_e32 v163, 0, v167
	ds_read_b128 v[180:183], v113
	ds_read_b128 v[184:187], v112 offset:2048
	ds_read_b128 v[188:191], v113 offset:2048
	ds_read_b64_tr_b16 v[112:113], v114 offset:49152
	ds_read_b64_tr_b16 v[114:115], v114 offset:51200
	ds_read_b64_tr_b16 v[192:193], v163 offset:49152
	ds_read_b64_tr_b16 v[194:195], v163 offset:51200
	v_add_u32_e32 v163, 0, v166
	s_waitcnt lgkmcnt(7)
	v_mfma_f32_16x16x32_bf16 v[204:207], v[176:179], v[52:55], 0
	v_add_u32_e32 v216, 0, v164
	ds_read_b64_tr_b16 v[196:197], v163 offset:49152
	ds_read_b64_tr_b16 v[198:199], v163 offset:51200
	v_add_u32_e32 v163, 0, v165
	v_add_u32_e32 v218, 0x18278, v216
	v_mov_b32_e32 v212, v174
	ds_read_b64_tr_b16 v[200:201], v163 offset:49152
	ds_read_b64_tr_b16 v[202:203], v163 offset:51200
	ds_read2_b32 v[174:175], v218 offset1:1
	s_add_i32 s10, s7, s35
	s_waitcnt lgkmcnt(11)
	v_mfma_f32_16x16x32_bf16 v[204:207], v[180:183], v[48:51], v[204:207]
	s_cmpk_lt_i32 s10, 0x80
	s_cselect_b64 s[10:11], -1, 0
	v_add_u32_e32 v163, s35, v152
	s_and_b64 s[50:51], s[44:45], s[10:11]
	v_cmp_gt_i32_e32 vcc, s96, v163
	s_waitcnt lgkmcnt(0)
	s_nop 1
	v_fmamk_f32 v175, v204, 0x3e38aa3b, v175
	s_and_b64 vcc, s[50:51], vcc
	v_cndmask_b32_e32 v204, v175, v236, vcc
	v_add_u32_e32 v175, 1, v163
	v_cmp_gt_i32_e64 s[10:11], s96, v175
	v_fmac_f32_e32 v174, 0x3e38aa3b, v205
	s_and_b64 s[10:11], s[50:51], s[10:11]
	v_add_u32_e32 v220, 0x18270, v216
	v_cndmask_b32_e64 v205, v174, v236, s[10:11]
	ds_read2_b32 v[174:175], v220 offset1:1
	v_mfma_f32_16x16x32_bf16 v[208:211], v[184:187], v[52:55], 0
	v_add_u32_e32 v215, 16, v163
	v_cmp_gt_i32_e64 s[16:17], s96, v215
	s_and_b64 s[16:17], s[50:51], s[16:17]
	s_waitcnt lgkmcnt(0)
	v_fmamk_f32 v175, v206, 0x3e38aa3b, v175
	v_add_u32_e32 v206, 2, v163
	v_cmp_gt_i32_e64 s[12:13], s96, v206
	s_and_b64 s[12:13], s[50:51], s[12:13]
	v_fmac_f32_e32 v174, 0x3e38aa3b, v207
	v_cndmask_b32_e64 v206, v175, v236, s[12:13]
	v_add_u32_e32 v175, 3, v163
	v_cmp_gt_i32_e64 s[14:15], s96, v175
	s_and_b64 s[14:15], s[50:51], s[14:15]
	v_mfma_f32_16x16x32_bf16 v[208:211], v[188:191], v[48:51], v[208:211]
	v_cndmask_b32_e64 v207, v174, v236, s[14:15]
	v_add_u32_e32 v174, 0x18238, v216
	ds_read2_b32 v[174:175], v174 offset1:1
	v_max3_f32 v213, v204, s54, v205
	v_max3_f32 v213, v213, v206, v207
	v_mfma_f32_16x16x32_bf16 v[176:179], v[176:179], v[60:63], 0
	s_add_i32 s35, s35, 32
	s_waitcnt lgkmcnt(0)
	v_fmamk_f32 v175, v208, 0x3e38aa3b, v175
	v_cndmask_b32_e64 v208, v175, v236, s[16:17]
	v_add_u32_e32 v175, 17, v163
	v_cmp_gt_i32_e64 s[18:19], s96, v175
	v_fmac_f32_e32 v174, 0x3e38aa3b, v209
	s_and_b64 s[18:19], s[50:51], s[18:19]
	v_cndmask_b32_e64 v219, v174, v236, s[18:19]
	v_add_u32_e32 v174, 0x18230, v216
	ds_read2_b32 v[174:175], v174 offset1:1
	v_max3_f32 v209, v213, v208, v219
	v_mfma_f32_16x16x32_bf16 v[176:179], v[180:183], v[56:59], v[176:179]
	v_add_u32_e32 v173, 0x1000, v173
	v_add_u32_e32 v171, 0x1000, v171
	s_waitcnt lgkmcnt(0)
	v_fmamk_f32 v175, v210, 0x3e38aa3b, v175
	v_add_u32_e32 v210, 18, v163
	v_add_u32_e32 v163, 19, v163
	v_cmp_gt_i32_e64 s[20:21], s96, v210
	v_cmp_gt_i32_e64 s[22:23], s96, v163
	s_and_b64 s[20:21], s[50:51], s[20:21]
	v_fmac_f32_e32 v174, 0x3e38aa3b, v211
	s_and_b64 s[22:23], s[50:51], s[22:23]
	v_cndmask_b32_e64 v175, v175, v236, s[20:21]
	v_cndmask_b32_e64 v163, v174, v236, s[22:23]
	v_max3_f32 v174, v209, v175, v163
	ds_bpermute_b32 v209, v123, v174
	v_mfma_f32_16x16x32_bf16 v[180:183], v[184:187], v[60:63], 0
	v_add_u32_e32 v164, 0xffffff80, v164
	v_add_u32_e32 v168, 0x1000, v168
	v_add_u32_e32 v167, 0x1000, v167
	s_waitcnt lgkmcnt(0)
	v_max_f32_e32 v209, v209, v209
	v_max_f32_e32 v174, v174, v209
	ds_bpermute_b32 v209, v121, v174
	v_mfma_f32_16x16x32_bf16 v[180:183], v[188:191], v[56:59], v[180:183]
	v_add_u32_e32 v166, 0x1000, v166
	v_add_u32_e32 v165, 0x1000, v165
	s_cmpk_eq_i32 s35, 0xa0
	s_waitcnt lgkmcnt(0)
	v_max3_f32 v174, v212, v174, v209
	v_sub_f32_e32 v204, v204, v174
	v_exp_f32_e32 v209, v204
	v_sub_f32_e32 v204, v205, v174
	v_exp_f32_e32 v211, v204
	v_sub_f32_e32 v204, v206, v174
	v_exp_f32_e32 v213, v204
	v_sub_f32_e32 v204, v207, v174
	v_exp_f32_e32 v215, v204
	v_sub_f32_e32 v204, v208, v174
	v_sub_f32_e32 v163, v163, v174
	v_exp_f32_e32 v217, v204
	v_sub_f32_e32 v204, v219, v174
	v_sub_f32_e32 v175, v175, v174
	v_exp_f32_e32 v241, v163
	v_add_u32_e32 v163, 0x182b8, v216
	v_exp_f32_e32 v219, v204
	v_exp_f32_e32 v221, v175
	v_cvt_pk_bf16_f32 v204, v209, v211
	v_cvt_pk_bf16_f32 v205, v213, v215
	v_cvt_pk_bf16_f32 v206, v217, v219
	v_cvt_pk_bf16_f32 v207, v221, v241
	ds_read2_b32 v[184:185], v163 offset1:1
	v_sub_f32_e32 v210, v212, v174
	v_exp_f32_e32 v242, v210
	s_waitcnt lgkmcnt(0)
	v_fmamk_f32 v163, v176, 0x3e38aa3b, v185
	v_add_u32_e32 v176, 0x182b0, v216
	v_fmac_f32_e32 v184, 0x3e38aa3b, v177
	ds_read2_b32 v[176:177], v176 offset1:1
	v_cndmask_b32_e32 v175, v163, v236, vcc
	v_cndmask_b32_e64 v184, v184, v236, s[10:11]
	v_max3_f32 v163, v175, s54, v184
	v_pk_mul_f32 v[110:111], v[110:111], v[242:243] op_sel_hi:[1,0]
	s_waitcnt lgkmcnt(0)
	v_fmamk_f32 v177, v178, 0x3e38aa3b, v177
	v_fmac_f32_e32 v176, 0x3e38aa3b, v179
	v_cndmask_b32_e64 v178, v177, v236, s[12:13]
	v_cndmask_b32_e64 v179, v176, v236, s[14:15]
	ds_read2_b32 v[176:177], v218 offset1:1
	v_max3_f32 v163, v163, v178, v179
	v_pk_mul_f32 v[108:109], v[108:109], v[242:243] op_sel_hi:[1,0]
	v_pk_mul_f32 v[106:107], v[106:107], v[242:243] op_sel_hi:[1,0]
	v_pk_mul_f32 v[104:105], v[104:105], v[242:243] op_sel_hi:[1,0]
	s_waitcnt lgkmcnt(0)
; __device__ __forceinline__ unsigned cvt_pk_bf16(float lo, float hi) { unsigned r; asm volatile("v_cvt_pk_bf16_f32 %0, %1, %2" : "=v"(r) : "v"(lo), "v"(hi)); return r; }
; __device__ __forceinline__ float fast_exp2(float x) { return __builtin_amdgcn_exp2f(x); }
; __device__ __forceinline__ void attn_phase(bf16_t* QKV, float* LSE, const float* rel_table, LAS unsigned char* lds, int bx, int Gd, int tid) {
;     ...
;                         S[kt][i] = sv; mx = fmaxf(mx, sv); }
;                 mx = fmaxf(mx, __shfl_xor(mx, 16)); mx = fmaxf(mx, __shfl_xor(mx, 32));
;                 const float mnew = fmaxf(mrun[qi], mx), alpha = fast_exp2(mrun[qi] - mnew); mrun[qi] = mnew;
;                 float ps = 0.f;
; #pragma unroll
;                 for (int kt = 0; kt < 2; ++kt)
; #pragma unroll
;                     for (int i = 0; i < 4; ++i) { const float p = fast_exp2(S[kt][i] - mnew); S[kt][i] = p; ps += p; }
;                 lsum[qi] = lsum[qi] * alpha + ps;
;                 u32x4 pw; pw.x = cvt_pk_bf16(S[0][0], S[0][1]); pw.y = cvt_pk_bf16(S[0][2], S[0][3]); pw.z = cvt_pk_bf16(S[1][0], S[1][1]); pw.w = cvt_pk_bf16(S[1][2], S[1][3]);
;                 const bf16x8 pf = __builtin_bit_cast(bf16x8, pw);
; #pragma unroll
;                 for (int cc = 0; cc < 4; ++cc) { O[qi][cc] = O[qi][cc] * alpha; O[qi][cc] = __builtin_amdgcn_mfma_f32_16x16x32_bf16(vf[cc], pf, O[qi][cc], 0, 0, 0); }
;             }
;         }
; #pragma unroll
;         for (int qi = 0; qi < 2; ++qi) {
;             float l = lsum[qi]; l += __shfl_xor(l, 16); l += __shfl_xor(l, 32);
;             const float inv = 1.0f / l;
;             const size_t tok = c.tok0 + (size_t)(c.N0 + 32 * w + 16 * qi + fr) * c.d;
;             bf16_t* op = QKV + tok * NQKV + c.qcol + 4 * G;
; #pragma unroll
;             for (int cc = 0; cc < 4; ++cc) { u32x2 o; o.x = cvt_pk_bf16(O[qi][cc][0] * inv, O[qi][cc][1] * inv); o.y = cvt_pk_bf16(O[qi][cc][2] * inv, O[qi][cc][3] * inv); *(u32x2*)(op + 16 * cc) = o; }
;             if (G == 0) LSE[(tok * 3 + c.g) * 8 + c.h] = mrun[qi] + __log2f(l);
	v_fmamk_f32 v177, v180, 0x3e38aa3b, v177
	v_fmac_f32_e32 v176, 0x3e38aa3b, v181
	v_cndmask_b32_e64 v180, v177, v236, s[16:17]
	v_cndmask_b32_e64 v181, v176, v236, s[18:19]
	ds_read2_b32 v[176:177], v220 offset1:1
	v_max3_f32 v163, v163, v180, v181
	v_pk_mul_f32 v[102:103], v[102:103], v[242:243] op_sel_hi:[1,0]
	v_pk_mul_f32 v[100:101], v[100:101], v[242:243] op_sel_hi:[1,0]
	v_pk_mul_f32 v[98:99], v[98:99], v[242:243] op_sel_hi:[1,0]
	s_waitcnt lgkmcnt(0)
	v_fmamk_f32 v177, v182, 0x3e38aa3b, v177
	v_fmac_f32_e32 v176, 0x3e38aa3b, v183
	v_cndmask_b32_e64 v177, v177, v236, s[20:21]
	v_cndmask_b32_e64 v176, v176, v236, s[22:23]
	v_max3_f32 v163, v163, v177, v176
	ds_bpermute_b32 v182, v123, v163
	v_pk_mul_f32 v[96:97], v[96:97], v[242:243] op_sel_hi:[1,0]
	v_mfma_f32_16x16x32_bf16 v[108:111], v[112:115], v[204:207], v[108:111]
	s_waitcnt lgkmcnt(0)
	v_max_f32_e32 v182, v182, v182
	v_max_f32_e32 v163, v163, v182
	ds_bpermute_b32 v182, v121, v163
	v_mfma_f32_16x16x32_bf16 v[104:107], v[192:195], v[204:207], v[104:107]
	s_waitcnt lgkmcnt(0)
	v_max3_f32 v163, v214, v163, v182
	v_sub_f32_e32 v175, v175, v163
	v_exp_f32_e32 v208, v175
	v_sub_f32_e32 v175, v184, v163
	v_exp_f32_e32 v210, v175
	v_sub_f32_e32 v175, v178, v163
	v_exp_f32_e32 v212, v175
	v_sub_f32_e32 v175, v179, v163
	v_sub_f32_e32 v182, v214, v163
	v_exp_f32_e32 v214, v175
	v_sub_f32_e32 v175, v180, v163
	v_exp_f32_e32 v216, v175
	v_sub_f32_e32 v175, v181, v163
	v_exp_f32_e32 v218, v175
	v_sub_f32_e32 v175, v177, v163
	v_exp_f32_e32 v220, v175
	v_sub_f32_e32 v175, v176, v163
	v_pk_add_f32 v[176:177], v[208:209], 0 op_sel_hi:[1,0]
	v_exp_f32_e32 v240, v175
	v_pk_add_f32 v[176:177], v[210:211], v[176:177]
	v_exp_f32_e32 v180, v182
	v_pk_add_f32 v[176:177], v[212:213], v[176:177]
	v_mov_b32_e32 v181, v242
	v_pk_add_f32 v[176:177], v[214:215], v[176:177]
	v_pk_mul_f32 v[94:95], v[94:95], v[180:181] op_sel_hi:[1,0]
	v_pk_add_f32 v[176:177], v[216:217], v[176:177]
	v_pk_mul_f32 v[92:93], v[92:93], v[180:181] op_sel_hi:[1,0]
	v_pk_add_f32 v[176:177], v[218:219], v[176:177]
	v_pk_mul_f32 v[90:91], v[90:91], v[180:181] op_sel_hi:[1,0]
	v_pk_add_f32 v[176:177], v[220:221], v[176:177]
	v_pk_mul_f32 v[88:89], v[88:89], v[180:181] op_sel_hi:[1,0]
	v_pk_add_f32 v[176:177], v[240:241], v[176:177]
	v_pk_mul_f32 v[86:87], v[86:87], v[180:181] op_sel_hi:[1,0]
	v_pk_mul_f32 v[84:85], v[84:85], v[180:181] op_sel_hi:[1,0]
	v_pk_mul_f32 v[82:83], v[82:83], v[180:181] op_sel_hi:[1,0]
	v_pk_mul_f32 v[80:81], v[80:81], v[180:181] op_sel_hi:[1,0]
	v_mfma_f32_16x16x32_bf16 v[100:103], v[196:199], v[204:207], v[100:103]
	v_fma_f32 v124, v124, v180, v176
	v_fma_f32 v125, v125, v181, v177
	v_cvt_pk_bf16_f32 v176, v208, v210
	v_cvt_pk_bf16_f32 v177, v212, v214
	v_mfma_f32_16x16x32_bf16 v[96:99], v[200:203], v[204:207], v[96:99]
	v_cvt_pk_bf16_f32 v178, v216, v218
	v_cvt_pk_bf16_f32 v179, v220, v240
	s_nop 0
	v_mfma_f32_16x16x32_bf16 v[92:95], v[112:115], v[176:179], v[92:95]
	v_mfma_f32_16x16x32_bf16 v[88:91], v[192:195], v[176:179], v[88:91]
	v_mfma_f32_16x16x32_bf16 v[84:87], v[196:199], v[176:179], v[84:87]
	v_mfma_f32_16x16x32_bf16 v[80:83], v[200:203], v[176:179], v[80:83]
	s_cbranch_scc0 .LBB0_119
	ds_bpermute_b32 v50, v123, v125
	v_add_u32_e32 v54, s29, v142
	s_ashr_i32 s35, s34, 31
	v_lshl_add_u64 v[48:49], s[34:35], 1, v[118:119]
	s_ashr_i32 s29, s28, 31
	s_waitcnt lgkmcnt(0)
	v_add_f32_e32 v50, v125, v50
	ds_bpermute_b32 v51, v121, v50
	s_lshl_b64 s[10:11], s[94:95], 2
	s_add_u32 s10, s26, s10
	s_addc_u32 s11, s27, s11
	s_waitcnt lgkmcnt(0)
	v_add_f32_e32 v56, v50, v51
	v_div_scale_f32 v50, s[12:13], v56, v56, 1.0
	v_rcp_f32_e32 v51, v50
	s_nop 0
	v_fma_f32 v52, -v50, v51, 1.0
	v_fmac_f32_e32 v51, v52, v51
	v_div_scale_f32 v52, vcc, 1.0, v56, 1.0
	v_mul_f32_e32 v53, v52, v51
	v_fma_f32 v55, -v50, v53, v52
	v_fmac_f32_e32 v53, v55, v51
	v_fma_f32 v50, -v50, v53, v52
	v_div_fmas_f32 v50, v50, v51, v53
	v_div_fixup_f32 v57, v50, v56, 1.0
	v_mov_b64_e32 v[50:51], s[30:31]
	v_mad_u64_u32 v[52:53], s[12:13], v54, s1, v[50:51]
	v_ashrrev_i32_e32 v55, 31, v54
	v_mov_b32_e32 v50, v53
	v_mad_u64_u32 v[58:59], s[12:13], v52, s53, v[48:49]
	v_mad_u64_u32 v[50:51], s[12:13], v55, s1, v[50:51]
	v_mov_b32_e32 v60, v59
	v_mad_u64_u32 v[60:61], s[12:13], v50, s53, v[60:61]
	v_mul_f32_e32 v51, v108, v57
	v_mul_f32_e32 v53, v109, v57
	v_mov_b32_e32 v59, v60
	v_cvt_pk_bf16_f32 v60, v51, v53
	v_mul_f32_e32 v51, v110, v57
	v_mul_f32_e32 v53, v111, v57
	v_cvt_pk_bf16_f32 v61, v51, v53
	v_mul_f32_e32 v51, v104, v57
	v_mul_f32_e32 v53, v105, v57
	global_store_dwordx2 v[58:59], v[60:61], off sc1
	v_cvt_pk_bf16_f32 v60, v51, v53
	v_mul_f32_e32 v51, v106, v57
	v_mul_f32_e32 v53, v107, v57
	v_cvt_pk_bf16_f32 v61, v51, v53
	v_mul_f32_e32 v51, v100, v57
	v_mul_f32_e32 v53, v101, v57
	global_store_dwordx2 v[58:59], v[60:61], off offset:32 sc1
	v_cvt_pk_bf16_f32 v60, v51, v53
	v_mul_f32_e32 v51, v102, v57
	v_mul_f32_e32 v53, v103, v57
	v_cvt_pk_bf16_f32 v61, v51, v53
	v_mul_f32_e32 v51, v96, v57
	v_mul_f32_e32 v53, v97, v57
	global_store_dwordx2 v[58:59], v[60:61], off offset:64 sc1
	v_cvt_pk_bf16_f32 v60, v51, v53
	v_mul_f32_e32 v51, v98, v57
	v_mul_f32_e32 v53, v99, v57
	v_cvt_pk_bf16_f32 v61, v51, v53
	global_store_dwordx2 v[58:59], v[60:61], off offset:96 sc1
	s_and_saveexec_b64 s[12:13], s[8:9]
	s_cbranch_execz .LBB0_122
	v_log_f32_e32 v51, v56
	v_mad_u64_u32 v[52:53], s[14:15], v52, 3, s[28:29]
	v_mov_b32_e32 v56, v53
	v_add_f32_e32 v57, v174, v51
	v_mad_u64_u32 v[50:51], s[14:15], v50, 3, v[56:57]
	v_mov_b32_e32 v53, v50
	v_lshlrev_b64 v[50:51], 5, v[52:53]
	v_lshl_add_u64 v[50:51], s[10:11], 0, v[50:51]
	global_store_dword v[50:51], v57, off sc1
; __device__ __forceinline__ unsigned cvt_pk_bf16(float lo, float hi) { unsigned r; asm volatile("v_cvt_pk_bf16_f32 %0, %1, %2" : "=v"(r) : "v"(lo), "v"(hi)); return r; }
; __device__ __forceinline__ void attn_phase(bf16_t* QKV, float* LSE, const float* rel_table, LAS unsigned char* lds, int bx, int Gd, int tid) {
;     ...
;         for (int qi = 0; qi < 2; ++qi) {
;             float l = lsum[qi]; l += __shfl_xor(l, 16); l += __shfl_xor(l, 32);
;             const float inv = 1.0f / l;
;             const size_t tok = c.tok0 + (size_t)(c.N0 + 32 * w + 16 * qi + fr) * c.d;
;             bf16_t* op = QKV + tok * NQKV + c.qcol + 4 * G;
; #pragma unroll
;             for (int cc = 0; cc < 4; ++cc) { u32x2 o; o.x = cvt_pk_bf16(O[qi][cc][0] * inv, O[qi][cc][1] * inv); o.y = cvt_pk_bf16(O[qi][cc][2] * inv, O[qi][cc][3] * inv); *(u32x2*)(op + 16 * cc) = o; }
;             if (G == 0) LSE[(tok * 3 + c.g) * 8 + c.h] = mrun[qi] + __log2f(l);
.LBB0_122:
	s_or_b64 exec, exec, s[12:13]
	ds_bpermute_b32 v50, v123, v124
	v_or_b32_e32 v52, 16, v54
	s_waitcnt lgkmcnt(0)
	v_add_f32_e32 v53, v124, v50
	ds_bpermute_b32 v54, v121, v53
	v_mov_b64_e32 v[50:51], s[30:31]
	v_mad_u64_u32 v[50:51], s[12:13], v52, s1, v[50:51]
	v_mov_b32_e32 v52, v51
	s_waitcnt lgkmcnt(0)
	v_add_f32_e32 v51, v53, v54
	v_div_scale_f32 v54, s[12:13], v51, v51, 1.0
	v_rcp_f32_e32 v56, v54
	v_mad_u64_u32 v[52:53], s[12:13], v55, s1, v[52:53]
	v_div_scale_f32 v53, vcc, 1.0, v51, 1.0
	v_fma_f32 v55, -v54, v56, 1.0
	v_fmac_f32_e32 v56, v55, v56
	v_mul_f32_e32 v55, v53, v56
	v_fma_f32 v57, -v54, v55, v53
	v_fmac_f32_e32 v55, v57, v56
	v_fma_f32 v53, -v54, v55, v53
	v_mad_u64_u32 v[48:49], s[12:13], v50, s53, v[48:49]
	v_div_fmas_f32 v53, v53, v56, v55
	v_mov_b32_e32 v54, v49
	v_div_fixup_f32 v53, v53, v51, 1.0
	v_mad_u64_u32 v[54:55], s[12:13], v52, s53, v[54:55]
	v_mov_b32_e32 v49, v54
	v_mul_f32_e32 v54, v92, v53
	v_mul_f32_e32 v55, v93, v53
	v_cvt_pk_bf16_f32 v54, v54, v55
	v_mul_f32_e32 v55, v94, v53
	v_mul_f32_e32 v56, v95, v53
	v_cvt_pk_bf16_f32 v55, v55, v56
	global_store_dwordx2 v[48:49], v[54:55], off sc1
	v_mul_f32_e32 v54, v88, v53
	v_mul_f32_e32 v55, v89, v53
	v_cvt_pk_bf16_f32 v54, v54, v55
	v_mul_f32_e32 v55, v90, v53
	v_mul_f32_e32 v56, v91, v53
	v_cvt_pk_bf16_f32 v55, v55, v56
	global_store_dwordx2 v[48:49], v[54:55], off offset:32 sc1
	v_mul_f32_e32 v54, v84, v53
	v_mul_f32_e32 v55, v85, v53
	v_cvt_pk_bf16_f32 v54, v54, v55
	v_mul_f32_e32 v55, v86, v53
	v_mul_f32_e32 v56, v87, v53
	v_cvt_pk_bf16_f32 v55, v55, v56
	global_store_dwordx2 v[48:49], v[54:55], off offset:64 sc1
	v_mul_f32_e32 v54, v80, v53
	v_mul_f32_e32 v55, v81, v53
	v_cvt_pk_bf16_f32 v54, v54, v55
	v_mul_f32_e32 v55, v82, v53
	v_mul_f32_e32 v53, v83, v53
	v_cvt_pk_bf16_f32 v55, v55, v53
	global_store_dwordx2 v[48:49], v[54:55], off offset:96 sc1
	s_and_saveexec_b64 s[12:13], s[8:9]
	s_cbranch_execz .LBB0_115
	v_log_f32_e32 v51, v51
	v_mad_u64_u32 v[48:49], s[14:15], v50, 3, s[28:29]
	v_mov_b32_e32 v50, v49
	v_add_f32_e32 v53, v163, v51
	v_mad_u64_u32 v[50:51], s[14:15], v52, 3, v[50:51]
	v_mov_b32_e32 v49, v50
	v_lshlrev_b64 v[48:49], 5, v[48:49]
	v_lshl_add_u64 v[48:49], s[10:11], 0, v[48:49]
	global_store_dword v[48:49], v53, off sc1
	s_branch .LBB0_115
